# attention tile loops: cross-half running-max exchange via v_permlane32_swap (VALU) instead of ds_bpermute + lgkmcnt wait (LDS round trip on the per-tile dependency chain)
# speedup vs baseline: 1.0076x; 1.0068x over previous
; #define LAS __attribute__((address_space(3)))
; #define MFMA32(a, b, c) __builtin_amdgcn_mfma_f32_32x32x16_bf16((a), (b), (c), 0, 0, 0)
; DI void attn_compute_sp4(const bf16x8 (&qf)[4], const bf16x8 (&kf)[4], const bf16x8 (&vf)[2][2], int kt, int d00, const float* lut, AttnSt& st, int win, int dmask) {
;     ...
;     for (int ks = 0; ks < 4; ++ks) sx = MFMA32(kf[ks], qf[ks], sx);
;     const int d0 = d00 - s0, e = d0 & 3;
;     const bool e0 = (e == 0), e1 = (e == 1), e2 = (e == 2);
;     const LAS float* lb = (const LAS float*)lut + (d0 - e - 20);
;     float sv[4]; float mx = NEGF;
; #pragma unroll
;     for (int g = 0; g < 4; ++g) {
;         const float x = e0 ? sx[4 * g] : (e1 ? sx[4 * g + 1] : (e2 ? sx[4 * g + 2] : sx[4 * g + 3]));
;         const int dist = d0 - (16 * (g >> 1) + 4 * (g & 1)) - e;
;         const bool v = ((unsigned)dist <= (unsigned)win) && ((dist & dmask) == 0);
;         const float bias = lb[20 - (16 * (g >> 1) + 4 * (g & 1))];
;         float sc = fmaf(x, SC2, bias);
;         sc = v ? sc : NEGF;
;         sv[g] = sc; mx = fmaxf(mx, sc);
;     }
;     mx = fmaxf(mx, __shfl_xor(mx, 32));
;     const float mnew = fmaxf(st.m, mx);
;     const float msafe = (mnew > -1e29f) ? mnew : 0.f;
;     if (__ballot(mnew > st.m) != 0ull) {
;         const float alpha = __builtin_amdgcn_exp2f(st.m - msafe);
;         st.l *= alpha; st.m = mnew;
; #pragma unroll
;         for (int i = 0; i < 16; ++i) { st.o0[i] *= alpha; st.o1[i] *= alpha; }
.LBB0_285:
	s_andn2_b64 vcc, exec, s[4:5]
	s_mov_b64 s[46:47], -1
	s_cbranch_vccnz .LBB0_289
	s_waitcnt lgkmcnt(0)
	v_mfma_f32_32x32x16_bf16 v[34:49], v[106:109], v[78:81], 0
	ds_read2_b32 v[50:51], v152 offset0:16 offset1:20
	ds_read2_b32 v[60:61], v152 offset1:4
	v_add_u32_e32 v52, v163, v151
	v_add_u32_e32 v53, 0x98, v52
	v_mov_b32_e32 v172, v150
	v_mov_b32_e32 v169, v153
	v_mfma_f32_32x32x16_bf16 v[34:49], v[110:113], v[74:77], v[34:49]
	v_mfma_f32_32x32x16_bf16 v[34:49], v[102:105], v[70:73], v[34:49]
	v_mfma_f32_32x32x16_bf16 v[34:49], v[98:101], v[66:69], v[34:49]
	s_nop 11
	v_cndmask_b32_e64 v54, v37, v36, s[38:39]
	v_cndmask_b32_e64 v56, v41, v40, s[38:39]
	v_cndmask_b32_e64 v57, v45, v44, s[38:39]
	v_cndmask_b32_e64 v58, v49, v48, s[38:39]
	v_cndmask_b32_e64 v54, v54, v35, s[40:41]
	v_cndmask_b32_e64 v56, v56, v39, s[40:41]
	v_cndmask_b32_e64 v57, v57, v43, s[40:41]
	v_cndmask_b32_e64 v58, v58, v47, s[40:41]
	v_cndmask_b32_e64 v54, v54, v34, s[42:43]
	v_cndmask_b32_e64 v56, v56, v38, s[42:43]
	v_cndmask_b32_e64 v57, v57, v42, s[42:43]
	v_cndmask_b32_e64 v58, v58, v46, s[42:43]
	s_waitcnt lgkmcnt(0)
	v_fmamk_f32 v51, v54, 0x3e38aa3b, v51
	v_cmp_gt_u32_e32 vcc, s31, v53
	v_add_u32_e32 v53, 0x94, v52
	s_nop 0
	v_cndmask_b32_e32 v170, v239, v51, vcc
	v_add_u32_e32 v55, 0x88, v52
	v_fmac_f32_e32 v50, 0x3e38aa3b, v56
	v_cmp_gt_u32_e32 vcc, s31, v53
	s_nop 1
	v_cndmask_b32_e32 v171, v239, v50, vcc
	v_max3_f32 v53, v170, s30, v171
	v_fmamk_f32 v61, v57, 0x3e38aa3b, v61
	v_cmp_gt_u32_e32 vcc, s31, v55
	s_nop 1
	v_cndmask_b32_e32 v173, v239, v61, vcc
	v_add_u32_e32 v35, 0x84, v52
	v_fmac_f32_e32 v60, 0x3e38aa3b, v58
	v_cmp_gt_u32_e32 vcc, s31, v35
	s_nop 1
	v_cndmask_b32_e32 v174, v239, v60, vcc
	v_max3_f32 v34, v53, v173, v174
	v_mov_b32_e32 v35, v34
	s_nop 1
	v_permlane32_swap_b32_e32 v35, v34
	v_mov_b64_e32 v[64:65], v[32:33]
	v_mov_b64_e32 v[62:63], v[30:31]
	v_mov_b64_e32 v[60:61], v[28:29]
	v_mov_b64_e32 v[58:59], v[26:27]
	s_waitcnt lgkmcnt(0)
	v_max3_f32 v176, v153, v34, v35
	v_cmp_lt_f32_e32 vcc, s12, v176
	v_mov_b64_e32 v[48:49], v[16:17]
	v_mov_b64_e32 v[56:57], v[24:25]
	v_cndmask_b32_e32 v175, 0, v176, vcc
	v_cmp_gt_f32_e32 vcc, v176, v153
	v_mov_b64_e32 v[54:55], v[22:23]
	v_mov_b64_e32 v[52:53], v[20:21]
	v_mov_b64_e32 v[50:51], v[18:19]
	v_mov_b64_e32 v[46:47], v[14:15]
	v_mov_b64_e32 v[44:45], v[12:13]
	v_mov_b64_e32 v[42:43], v[10:11]
	v_mov_b64_e32 v[40:41], v[8:9]
	v_mov_b64_e32 v[38:39], v[6:7]
	v_mov_b64_e32 v[36:37], v[4:5]
	v_mov_b64_e32 v[34:35], v[2:3]
	s_cbranch_vccz .LBB0_288
	v_sub_f32_e32 v34, v153, v175
	v_exp_f32_e32 v50, v34
	v_mov_b32_e32 v169, v176
	v_mul_f32_e32 v172, v150, v50
	v_pk_mul_f32 v[48:49], v[16:17], v[50:51] op_sel_hi:[1,0]
	v_pk_mul_f32 v[46:47], v[14:15], v[50:51] op_sel_hi:[1,0]
	v_pk_mul_f32 v[44:45], v[12:13], v[50:51] op_sel_hi:[1,0]
	v_pk_mul_f32 v[42:43], v[10:11], v[50:51] op_sel_hi:[1,0]
	v_pk_mul_f32 v[40:41], v[8:9], v[50:51] op_sel_hi:[1,0]
	v_pk_mul_f32 v[38:39], v[6:7], v[50:51] op_sel_hi:[1,0]
	v_pk_mul_f32 v[36:37], v[4:5], v[50:51] op_sel_hi:[1,0]
	v_pk_mul_f32 v[34:35], v[2:3], v[50:51] op_sel_hi:[1,0]
	v_pk_mul_f32 v[64:65], v[32:33], v[50:51] op_sel_hi:[1,0]
	v_pk_mul_f32 v[62:63], v[30:31], v[50:51] op_sel_hi:[1,0]
	v_pk_mul_f32 v[60:61], v[28:29], v[50:51] op_sel_hi:[1,0]
	v_pk_mul_f32 v[58:59], v[26:27], v[50:51] op_sel_hi:[1,0]
	v_pk_mul_f32 v[56:57], v[24:25], v[50:51] op_sel_hi:[1,0]
	v_pk_mul_f32 v[54:55], v[22:23], v[50:51] op_sel_hi:[1,0]
	v_pk_mul_f32 v[52:53], v[20:21], v[50:51] op_sel_hi:[1,0]
	v_pk_mul_f32 v[50:51], v[18:19], v[50:51] op_sel_hi:[1,0]

; #define MFMA32(a, b, c) __builtin_amdgcn_mfma_f32_32x32x16_bf16((a), (b), (c), 0, 0, 0)
; template <int MODE, bool UNI>
; DI void attn_compute(const bf16x8 (&qf)[4], const bf16x8 (&kf)[4], const bf16x8 (&vf)[2][2], int kt, int d00, const float* lut, float ubias, AttnSt& st,
;                      unsigned W, int win, int dmask, bool lane_sel) {
;     ...
;         for (int i = 0; i < 16; ++i) { const int ci = 16 * (i >> 3) + (i & 7); bia[i] = (MODE == 4) ? lb[16 * (23 - ci)] : lb[23 - ci]; }
;     }
;     f32x16 sx;
; #pragma unroll
;     for (int i = 0; i < 16; ++i) sx[i] = 0.f;
; #pragma unroll
;     for (int ks = 0; ks < 4; ++ks) sx = MFMA32(kf[ks], qf[ks], sx);
;     asm volatile("s_waitcnt lgkmcnt(0)" ::: "memory");
;     float sv[16]; float mx = NEGF;
; #pragma unroll
;     for (int i = 0; i < 16; ++i) {
;         const int ci = 16 * (i >> 3) + (i & 7);
;         const int dist = d0 - ci;
;         bool v;
;         if (MODE == 0) v = ((W >> ci) & 1u) != 0u;
;         else if (MODE == 1) v = ((unsigned)dist <= (unsigned)win) && ((dist & dmask) == 0);
;         else if (MODE == 2) v = lane_sel;
;         else v = dist >= 0;
;         const float bias = UNI ? ubias : bia[i];
;         float s = fmaf(sx[i], SC2, bias);
;         if (MODE == 0) { const unsigned t = (unsigned)__builtin_amdgcn_sbfe((int)W, ci, 1);
;             s = __uint_as_float((__float_as_uint(s) & t) | (__float_as_uint(NEGF) & ~t)); }
;         else s = v ? s : NEGF;
;         sv[i] = s; mx = fmaxf(mx, s);
;     }
;     mx = fmaxf(mx, __shfl_xor(mx, 32));
;     const float mnew = fmaxf(st.m, mx);
;     const float msafe = (mnew > -1e29f) ? mnew : 0.f;
;     if (__ballot(mnew > st.m) != 0ull) {
;         const float alpha = __builtin_amdgcn_exp2f(st.m - msafe);
;         st.l *= alpha; st.m = mnew;
; #pragma unroll
;         for (int i = 0; i < 16; ++i) { st.o0[i] *= alpha; st.o1[i] *= alpha; }
;     }
.LBB0_289:
	s_and_b64 vcc, exec, s[46:47]
	s_cbranch_vccz .LBB0_294
	s_waitcnt lgkmcnt(0)
	v_mfma_f32_32x32x16_bf16 v[34:49], v[106:109], v[78:81], 0
	ds_read2_b32 v[50:51], v0 offset0:22 offset1:23
	ds_read2_b32 v[52:53], v0 offset0:20 offset1:21
	ds_read2_b32 v[54:55], v0 offset0:18 offset1:19
	ds_read2_b32 v[56:57], v0 offset0:16 offset1:17
	v_add_u32_e32 v106, 0x98, v151
	v_cmp_gt_u32_e32 vcc, s95, v106
	v_add_u32_e32 v107, 18, v151
	ds_read2_b32 v[58:59], v0 offset0:6 offset1:7
	ds_read2_b32 v[60:61], v0 offset0:4 offset1:5
	ds_read2_b32 v[62:63], v0 offset0:2 offset1:3
	ds_read2_b32 v[64:65], v0 offset1:1
	s_waitcnt lgkmcnt(0)
	v_mfma_f32_32x32x16_bf16 v[34:49], v[110:113], v[74:77], v[34:49]
	v_mfma_f32_32x32x16_bf16 v[34:49], v[102:105], v[70:73], v[34:49]
	v_add_u32_e32 v102, 22, v151
	v_add_u32_e32 v103, 21, v151
	v_add_u32_e32 v104, 20, v151
	v_add_u32_e32 v105, 19, v151
	v_mfma_f32_32x32x16_bf16 v[34:49], v[98:101], v[66:69], v[34:49]
	s_waitcnt lgkmcnt(0)
	s_nop 10
	v_fmamk_f32 v34, v34, 0x3e38aa3b, v51
	v_fmac_f32_e32 v50, 0x3e38aa3b, v35
	v_cndmask_b32_e32 v35, v239, v34, vcc
	v_cmp_lt_u32_e32 vcc, s13, v102
	v_fmamk_f32 v51, v36, 0x3e38aa3b, v53
	v_fmac_f32_e32 v52, 0x3e38aa3b, v37
	v_cndmask_b32_e32 v36, v239, v50, vcc
	v_cmp_lt_u32_e32 vcc, s13, v103
	v_fmamk_f32 v38, v38, 0x3e38aa3b, v55
	v_fmac_f32_e32 v54, 0x3e38aa3b, v39
	v_cndmask_b32_e32 v37, v239, v51, vcc
	v_cmp_lt_u32_e32 vcc, s13, v104
	v_add_u32_e32 v51, 17, v151
	v_fmamk_f32 v40, v40, 0x3e38aa3b, v57
	v_cndmask_b32_e32 v34, v239, v52, vcc
	v_cmp_lt_u32_e32 vcc, s13, v105
	v_fmac_f32_e32 v56, 0x3e38aa3b, v41
	v_fmamk_f32 v42, v42, 0x3e38aa3b, v59
	v_cndmask_b32_e32 v39, v239, v38, vcc
	v_cmp_lt_u32_e32 vcc, s13, v107
	v_max3_f32 v38, v35, s30, v36
	v_fmac_f32_e32 v58, 0x3e38aa3b, v43
	v_cndmask_b32_e32 v50, v239, v54, vcc
	v_cmp_lt_u32_e32 vcc, s13, v51
	v_max3_f32 v38, v38, v37, v34
	v_fmamk_f32 v44, v44, 0x3e38aa3b, v61
	v_cndmask_b32_e32 v51, v239, v40, vcc
	v_add_u32_e32 v40, 16, v151
	v_cmp_lt_u32_e32 vcc, s13, v40
	v_add_u32_e32 v40, 7, v151
	v_max3_f32 v38, v38, v39, v50
	v_cndmask_b32_e32 v41, v239, v56, vcc
	v_cmp_lt_u32_e32 vcc, s13, v40
	v_add_u32_e32 v40, 6, v151
	v_fmac_f32_e32 v60, 0x3e38aa3b, v45
	v_cndmask_b32_e32 v42, v239, v42, vcc
	v_cmp_lt_u32_e32 vcc, s13, v40
	v_add_u32_e32 v40, 5, v151
	v_max3_f32 v38, v38, v51, v41
	v_cndmask_b32_e32 v43, v239, v58, vcc
	v_cmp_lt_u32_e32 vcc, s13, v40
	v_add_u32_e32 v40, 4, v151
	v_fmamk_f32 v46, v46, 0x3e38aa3b, v63
	v_cndmask_b32_e32 v44, v239, v44, vcc
	v_cmp_lt_u32_e32 vcc, s13, v40
	v_add_u32_e32 v40, 3, v151
	v_max3_f32 v38, v38, v42, v43
	v_cndmask_b32_e32 v45, v239, v60, vcc
	v_cmp_lt_u32_e32 vcc, s13, v40
	v_add_u32_e32 v40, 2, v151
	v_fmac_f32_e32 v62, 0x3e38aa3b, v47
	v_cndmask_b32_e32 v46, v239, v46, vcc
	v_cmp_lt_u32_e32 vcc, s13, v40
	v_max3_f32 v38, v38, v44, v45
	v_fmamk_f32 v48, v48, 0x3e38aa3b, v65
	v_cndmask_b32_e32 v47, v239, v62, vcc
	v_max3_f32 v40, v38, v46, v47
	v_add_u32_e32 v38, 1, v151
	v_cmp_lt_u32_e32 vcc, s13, v38
	v_fmac_f32_e32 v64, 0x3e38aa3b, v49
	s_nop 0
	v_cndmask_b32_e32 v48, v239, v48, vcc
	v_cmp_lt_u32_e32 vcc, s13, v151
	s_nop 1
	v_cndmask_b32_e32 v38, v239, v64, vcc
	v_max3_f32 v40, v40, v48, v38
	v_mov_b32_e32 v49, v40
	s_nop 1
	v_permlane32_swap_b32_e32 v49, v40
	s_waitcnt lgkmcnt(0)
	v_max3_f32 v169, v153, v40, v49
	v_cmp_lt_f32_e32 vcc, s12, v169
	s_nop 1
	v_cndmask_b32_e32 v40, 0, v169, vcc
	v_cmp_gt_f32_e32 vcc, v169, v153
	s_cbranch_vccz .LBB0_292
	v_sub_f32_e32 v49, v153, v40
	v_exp_f32_e32 v52, v49
	s_nop 0
	v_mul_f32_e32 v150, v150, v52
	v_pk_mul_f32 v[16:17], v[16:17], v[52:53] op_sel_hi:[1,0]
	v_pk_mul_f32 v[14:15], v[14:15], v[52:53] op_sel_hi:[1,0]
	v_pk_mul_f32 v[12:13], v[12:13], v[52:53] op_sel_hi:[1,0]
	v_pk_mul_f32 v[10:11], v[10:11], v[52:53] op_sel_hi:[1,0]
	v_pk_mul_f32 v[8:9], v[8:9], v[52:53] op_sel_hi:[1,0]
	v_pk_mul_f32 v[6:7], v[6:7], v[52:53] op_sel_hi:[1,0]
	v_pk_mul_f32 v[4:5], v[4:5], v[52:53] op_sel_hi:[1,0]
	v_pk_mul_f32 v[2:3], v[2:3], v[52:53] op_sel_hi:[1,0]
	v_pk_mul_f32 v[32:33], v[32:33], v[52:53] op_sel_hi:[1,0]
	v_pk_mul_f32 v[30:31], v[30:31], v[52:53] op_sel_hi:[1,0]
	v_pk_mul_f32 v[28:29], v[28:29], v[52:53] op_sel_hi:[1,0]
	v_pk_mul_f32 v[26:27], v[26:27], v[52:53] op_sel_hi:[1,0]
	v_pk_mul_f32 v[24:25], v[24:25], v[52:53] op_sel_hi:[1,0]
	v_pk_mul_f32 v[22:23], v[22:23], v[52:53] op_sel_hi:[1,0]
	v_pk_mul_f32 v[20:21], v[20:21], v[52:53] op_sel_hi:[1,0]
	v_pk_mul_f32 v[18:19], v[18:19], v[52:53] op_sel_hi:[1,0]
	s_branch .LBB0_293

; #define LAS __attribute__((address_space(3)))
; #define MFMA32(a, b, c) __builtin_amdgcn_mfma_f32_32x32x16_bf16((a), (b), (c), 0, 0, 0)
; DI void attn_compute_sp4(const bf16x8 (&qf)[4], const bf16x8 (&kf)[4], const bf16x8 (&vf)[2][2], int kt, int d00, const float* lut, AttnSt& st, int win, int dmask) {
;     ...
;     for (int ks = 0; ks < 4; ++ks) sx = MFMA32(kf[ks], qf[ks], sx);
;     const int d0 = d00 - s0, e = d0 & 3;
;     const bool e0 = (e == 0), e1 = (e == 1), e2 = (e == 2);
;     const LAS float* lb = (const LAS float*)lut + (d0 - e - 20);
;     float sv[4]; float mx = NEGF;
; #pragma unroll
;     for (int g = 0; g < 4; ++g) {
;         const float x = e0 ? sx[4 * g] : (e1 ? sx[4 * g + 1] : (e2 ? sx[4 * g + 2] : sx[4 * g + 3]));
;         const int dist = d0 - (16 * (g >> 1) + 4 * (g & 1)) - e;
;         const bool v = ((unsigned)dist <= (unsigned)win) && ((dist & dmask) == 0);
;         const float bias = lb[20 - (16 * (g >> 1) + 4 * (g & 1))];
;         float sc = fmaf(x, SC2, bias);
;         sc = v ? sc : NEGF;
;         sv[g] = sc; mx = fmaxf(mx, sc);
;     }
;     mx = fmaxf(mx, __shfl_xor(mx, 32));
;     const float mnew = fmaxf(st.m, mx);
;     const float msafe = (mnew > -1e29f) ? mnew : 0.f;
;     if (__ballot(mnew > st.m) != 0ull) {
;         const float alpha = __builtin_amdgcn_exp2f(st.m - msafe);
;         st.l *= alpha; st.m = mnew;
; #pragma unroll
;         for (int i = 0; i < 16; ++i) { st.o0[i] *= alpha; st.o1[i] *= alpha; }
.LBB0_304:
	s_andn2_b64 vcc, exec, s[4:5]
	s_mov_b64 s[46:47], -1
	s_cbranch_vccnz .LBB0_308
	s_waitcnt lgkmcnt(0)
	v_mfma_f32_32x32x16_bf16 v[2:17], v[106:109], v[78:81], 0
	ds_read2_b32 v[50:51], v171 offset0:16 offset1:20
	ds_read2_b32 v[60:61], v171 offset1:4
	v_add_u32_e32 v52, v163, v170
	v_add_u32_e32 v53, 0x98, v52
	v_mov_b32_e32 v176, v149
	v_mov_b32_e32 v173, v172
	v_mfma_f32_32x32x16_bf16 v[2:17], v[110:113], v[74:77], v[2:17]
	v_mfma_f32_32x32x16_bf16 v[2:17], v[102:105], v[70:73], v[2:17]
	v_mfma_f32_32x32x16_bf16 v[2:17], v[98:101], v[66:69], v[2:17]
	s_nop 11
	v_cndmask_b32_e64 v54, v5, v4, s[38:39]
	v_cndmask_b32_e64 v56, v9, v8, s[38:39]
	v_cndmask_b32_e64 v57, v13, v12, s[38:39]
	v_cndmask_b32_e64 v58, v17, v16, s[38:39]
	v_cndmask_b32_e64 v54, v54, v3, s[40:41]
	v_cndmask_b32_e64 v56, v56, v7, s[40:41]
	v_cndmask_b32_e64 v57, v57, v11, s[40:41]
	v_cndmask_b32_e64 v58, v58, v15, s[40:41]
	v_cndmask_b32_e64 v54, v54, v2, s[42:43]
	v_cndmask_b32_e64 v56, v56, v6, s[42:43]
	v_cndmask_b32_e64 v57, v57, v10, s[42:43]
	v_cndmask_b32_e64 v58, v58, v14, s[42:43]
	s_waitcnt lgkmcnt(0)
	v_fmamk_f32 v51, v54, 0x3e38aa3b, v51
	v_cmp_gt_u32_e32 vcc, s31, v53
	v_add_u32_e32 v53, 0x94, v52
	s_nop 0
	v_cndmask_b32_e32 v174, v239, v51, vcc
	v_add_u32_e32 v55, 0x88, v52
	v_fmac_f32_e32 v50, 0x3e38aa3b, v56
	v_cmp_gt_u32_e32 vcc, s31, v53
	s_nop 1
	v_cndmask_b32_e32 v175, v239, v50, vcc
	v_max3_f32 v53, v174, s30, v175
	v_fmamk_f32 v61, v57, 0x3e38aa3b, v61
	v_cmp_gt_u32_e32 vcc, s31, v55
	s_nop 1
	v_cndmask_b32_e32 v177, v239, v61, vcc
	v_add_u32_e32 v3, 0x84, v52
	v_fmac_f32_e32 v60, 0x3e38aa3b, v58
	v_cmp_gt_u32_e32 vcc, s31, v3
	s_nop 1
	v_cndmask_b32_e32 v178, v239, v60, vcc
	v_max3_f32 v2, v53, v177, v178
	v_mov_b32_e32 v3, v2
	s_nop 1
	v_permlane32_swap_b32_e32 v3, v2
	v_mov_b64_e32 v[64:65], v[48:49]
	v_mov_b64_e32 v[62:63], v[46:47]
	v_mov_b64_e32 v[60:61], v[44:45]
	v_mov_b64_e32 v[58:59], v[42:43]
	s_waitcnt lgkmcnt(0)
	v_max3_f32 v180, v172, v2, v3
	v_cmp_lt_f32_e32 vcc, s12, v180
	v_mov_b64_e32 v[2:3], v[18:19]
	v_mov_b64_e32 v[4:5], v[20:21]
	v_cndmask_b32_e32 v179, 0, v180, vcc
	v_cmp_gt_f32_e32 vcc, v180, v172
	v_mov_b64_e32 v[6:7], v[22:23]
	v_mov_b64_e32 v[8:9], v[24:25]
	v_mov_b64_e32 v[10:11], v[26:27]
	v_mov_b64_e32 v[12:13], v[28:29]
	v_mov_b64_e32 v[14:15], v[30:31]
	v_mov_b64_e32 v[16:17], v[32:33]
	v_mov_b64_e32 v[56:57], v[40:41]
	v_mov_b64_e32 v[54:55], v[38:39]
	v_mov_b64_e32 v[52:53], v[36:37]
	v_mov_b64_e32 v[50:51], v[34:35]
	s_cbranch_vccz .LBB0_307
	v_sub_f32_e32 v2, v172, v179
	v_exp_f32_e32 v2, v2
	v_mov_b32_e32 v173, v180
	v_mul_f32_e32 v176, v149, v2
	v_pk_mul_f32 v[64:65], v[48:49], v[2:3] op_sel_hi:[1,0]
	v_pk_mul_f32 v[62:63], v[46:47], v[2:3] op_sel_hi:[1,0]
	v_pk_mul_f32 v[60:61], v[44:45], v[2:3] op_sel_hi:[1,0]
	v_pk_mul_f32 v[58:59], v[42:43], v[2:3] op_sel_hi:[1,0]
	v_pk_mul_f32 v[56:57], v[40:41], v[2:3] op_sel_hi:[1,0]
	v_pk_mul_f32 v[54:55], v[38:39], v[2:3] op_sel_hi:[1,0]
	v_pk_mul_f32 v[52:53], v[36:37], v[2:3] op_sel_hi:[1,0]
	v_pk_mul_f32 v[50:51], v[34:35], v[2:3] op_sel_hi:[1,0]
	v_pk_mul_f32 v[16:17], v[32:33], v[2:3] op_sel_hi:[1,0]
	v_pk_mul_f32 v[14:15], v[30:31], v[2:3] op_sel_hi:[1,0]
	v_pk_mul_f32 v[12:13], v[28:29], v[2:3] op_sel_hi:[1,0]
	v_pk_mul_f32 v[10:11], v[26:27], v[2:3] op_sel_hi:[1,0]
	v_pk_mul_f32 v[8:9], v[24:25], v[2:3] op_sel_hi:[1,0]
	v_pk_mul_f32 v[6:7], v[22:23], v[2:3] op_sel_hi:[1,0]
	v_pk_mul_f32 v[4:5], v[20:21], v[2:3] op_sel_hi:[1,0]
	v_pk_mul_f32 v[2:3], v[18:19], v[2:3] op_sel_hi:[1,0]

; #define MFMA32(a, b, c) __builtin_amdgcn_mfma_f32_32x32x16_bf16((a), (b), (c), 0, 0, 0)
; template <int MODE, bool UNI>
; DI void attn_compute(const bf16x8 (&qf)[4], const bf16x8 (&kf)[4], const bf16x8 (&vf)[2][2], int kt, int d00, const float* lut, float ubias, AttnSt& st,
;                      unsigned W, int win, int dmask, bool lane_sel) {
;     ...
;         for (int i = 0; i < 16; ++i) { const int ci = 16 * (i >> 3) + (i & 7); bia[i] = (MODE == 4) ? lb[16 * (23 - ci)] : lb[23 - ci]; }
;     }
;     f32x16 sx;
; #pragma unroll
;     for (int i = 0; i < 16; ++i) sx[i] = 0.f;
; #pragma unroll
;     for (int ks = 0; ks < 4; ++ks) sx = MFMA32(kf[ks], qf[ks], sx);
;     asm volatile("s_waitcnt lgkmcnt(0)" ::: "memory");
;     float sv[16]; float mx = NEGF;
; #pragma unroll
;     for (int i = 0; i < 16; ++i) {
;         const int ci = 16 * (i >> 3) + (i & 7);
;         const int dist = d0 - ci;
;         bool v;
;         if (MODE == 0) v = ((W >> ci) & 1u) != 0u;
;         else if (MODE == 1) v = ((unsigned)dist <= (unsigned)win) && ((dist & dmask) == 0);
;         else if (MODE == 2) v = lane_sel;
;         else v = dist >= 0;
;         const float bias = UNI ? ubias : bia[i];
;         float s = fmaf(sx[i], SC2, bias);
;         if (MODE == 0) { const unsigned t = (unsigned)__builtin_amdgcn_sbfe((int)W, ci, 1);
;             s = __uint_as_float((__float_as_uint(s) & t) | (__float_as_uint(NEGF) & ~t)); }
;         else s = v ? s : NEGF;
;         sv[i] = s; mx = fmaxf(mx, s);
;     }
;     mx = fmaxf(mx, __shfl_xor(mx, 32));
;     const float mnew = fmaxf(st.m, mx);
;     const float msafe = (mnew > -1e29f) ? mnew : 0.f;
;     if (__ballot(mnew > st.m) != 0ull) {
;         const float alpha = __builtin_amdgcn_exp2f(st.m - msafe);
;         st.l *= alpha; st.m = mnew;
; #pragma unroll
;         for (int i = 0; i < 16; ++i) { st.o0[i] *= alpha; st.o1[i] *= alpha; }
;     }
.LBB0_308:
	s_and_b64 vcc, exec, s[46:47]
	s_cbranch_vccz .LBB0_313
	s_waitcnt lgkmcnt(0)
	v_mfma_f32_32x32x16_bf16 v[2:17], v[106:109], v[78:81], 0
	ds_read2_b32 v[50:51], v169 offset0:22 offset1:23
	ds_read2_b32 v[52:53], v169 offset0:20 offset1:21
	ds_read2_b32 v[54:55], v169 offset0:18 offset1:19
	ds_read2_b32 v[56:57], v169 offset0:16 offset1:17
	v_add_u32_e32 v106, 0x98, v170
	v_cmp_gt_u32_e32 vcc, s95, v106
	v_add_u32_e32 v107, 18, v170
	ds_read2_b32 v[58:59], v169 offset0:6 offset1:7
	ds_read2_b32 v[60:61], v169 offset0:4 offset1:5
	ds_read2_b32 v[62:63], v169 offset0:2 offset1:3
	ds_read2_b32 v[64:65], v169 offset1:1
	s_waitcnt lgkmcnt(0)
	v_mfma_f32_32x32x16_bf16 v[2:17], v[110:113], v[74:77], v[2:17]
	v_mfma_f32_32x32x16_bf16 v[2:17], v[102:105], v[70:73], v[2:17]
	v_add_u32_e32 v102, 22, v170
	v_add_u32_e32 v103, 21, v170
	v_add_u32_e32 v104, 20, v170
	v_add_u32_e32 v105, 19, v170
	v_mfma_f32_32x32x16_bf16 v[2:17], v[98:101], v[66:69], v[2:17]
	s_waitcnt lgkmcnt(0)
	s_nop 10
	v_fmamk_f32 v2, v2, 0x3e38aa3b, v51
	v_fmac_f32_e32 v50, 0x3e38aa3b, v3
	v_cndmask_b32_e32 v3, v239, v2, vcc
	v_cmp_lt_u32_e32 vcc, s13, v102
	v_fmamk_f32 v51, v4, 0x3e38aa3b, v53
	v_fmac_f32_e32 v52, 0x3e38aa3b, v5
	v_cndmask_b32_e32 v4, v239, v50, vcc
	v_cmp_lt_u32_e32 vcc, s13, v103
	v_fmamk_f32 v6, v6, 0x3e38aa3b, v55
	v_fmac_f32_e32 v54, 0x3e38aa3b, v7
	v_cndmask_b32_e32 v5, v239, v51, vcc
	v_cmp_lt_u32_e32 vcc, s13, v104
	v_add_u32_e32 v51, 17, v170
	v_fmamk_f32 v8, v8, 0x3e38aa3b, v57
	v_cndmask_b32_e32 v2, v239, v52, vcc
	v_cmp_lt_u32_e32 vcc, s13, v105
	v_fmac_f32_e32 v56, 0x3e38aa3b, v9
	v_fmamk_f32 v10, v10, 0x3e38aa3b, v59
	v_cndmask_b32_e32 v7, v239, v6, vcc
	v_cmp_lt_u32_e32 vcc, s13, v107
	v_max3_f32 v6, v3, s30, v4
	v_fmac_f32_e32 v58, 0x3e38aa3b, v11
	v_cndmask_b32_e32 v50, v239, v54, vcc
	v_cmp_lt_u32_e32 vcc, s13, v51
	v_max3_f32 v6, v6, v5, v2
	v_fmamk_f32 v12, v12, 0x3e38aa3b, v61
	v_cndmask_b32_e32 v51, v239, v8, vcc
	v_add_u32_e32 v8, 16, v170
	v_cmp_lt_u32_e32 vcc, s13, v8
	v_add_u32_e32 v8, 7, v170
	v_max3_f32 v6, v6, v7, v50
	v_cndmask_b32_e32 v9, v239, v56, vcc
	v_cmp_lt_u32_e32 vcc, s13, v8
	v_add_u32_e32 v8, 6, v170
	v_fmac_f32_e32 v60, 0x3e38aa3b, v13
	v_cndmask_b32_e32 v10, v239, v10, vcc
	v_cmp_lt_u32_e32 vcc, s13, v8
	v_add_u32_e32 v8, 5, v170
	v_max3_f32 v6, v6, v51, v9
	v_cndmask_b32_e32 v11, v239, v58, vcc
	v_cmp_lt_u32_e32 vcc, s13, v8
	v_add_u32_e32 v8, 4, v170
	v_fmamk_f32 v14, v14, 0x3e38aa3b, v63
	v_cndmask_b32_e32 v12, v239, v12, vcc
	v_cmp_lt_u32_e32 vcc, s13, v8
	v_add_u32_e32 v8, 3, v170
	v_max3_f32 v6, v6, v10, v11
	v_cndmask_b32_e32 v13, v239, v60, vcc
	v_cmp_lt_u32_e32 vcc, s13, v8
	v_add_u32_e32 v8, 2, v170
	v_fmac_f32_e32 v62, 0x3e38aa3b, v15
	v_cndmask_b32_e32 v14, v239, v14, vcc
	v_cmp_lt_u32_e32 vcc, s13, v8
	v_max3_f32 v6, v6, v12, v13
	v_fmamk_f32 v16, v16, 0x3e38aa3b, v65
	v_cndmask_b32_e32 v15, v239, v62, vcc
	v_max3_f32 v8, v6, v14, v15
	v_add_u32_e32 v6, 1, v170
	v_cmp_lt_u32_e32 vcc, s13, v6
	v_fmac_f32_e32 v64, 0x3e38aa3b, v17
	s_nop 0
	v_cndmask_b32_e32 v16, v239, v16, vcc
	v_cmp_lt_u32_e32 vcc, s13, v170
	s_nop 1
	v_cndmask_b32_e32 v6, v239, v64, vcc
	v_max3_f32 v8, v8, v16, v6
	v_mov_b32_e32 v17, v8
	s_nop 1
	v_permlane32_swap_b32_e32 v17, v8
	s_waitcnt lgkmcnt(0)
	v_max3_f32 v173, v172, v8, v17
	v_cmp_lt_f32_e32 vcc, s12, v173
	s_nop 1
	v_cndmask_b32_e32 v8, 0, v173, vcc
	v_cmp_gt_f32_e32 vcc, v173, v172
	s_cbranch_vccz .LBB0_311
	v_sub_f32_e32 v17, v172, v8
	v_exp_f32_e32 v52, v17
	s_nop 0
	v_mul_f32_e32 v149, v149, v52
	v_pk_mul_f32 v[48:49], v[48:49], v[52:53] op_sel_hi:[1,0]
	v_pk_mul_f32 v[46:47], v[46:47], v[52:53] op_sel_hi:[1,0]
	v_pk_mul_f32 v[44:45], v[44:45], v[52:53] op_sel_hi:[1,0]
	v_pk_mul_f32 v[42:43], v[42:43], v[52:53] op_sel_hi:[1,0]
	v_pk_mul_f32 v[40:41], v[40:41], v[52:53] op_sel_hi:[1,0]
	v_pk_mul_f32 v[38:39], v[38:39], v[52:53] op_sel_hi:[1,0]
	v_pk_mul_f32 v[36:37], v[36:37], v[52:53] op_sel_hi:[1,0]
	v_pk_mul_f32 v[34:35], v[34:35], v[52:53] op_sel_hi:[1,0]
	v_pk_mul_f32 v[32:33], v[32:33], v[52:53] op_sel_hi:[1,0]
	v_pk_mul_f32 v[30:31], v[30:31], v[52:53] op_sel_hi:[1,0]
	v_pk_mul_f32 v[28:29], v[28:29], v[52:53] op_sel_hi:[1,0]
	v_pk_mul_f32 v[26:27], v[26:27], v[52:53] op_sel_hi:[1,0]
	v_pk_mul_f32 v[24:25], v[24:25], v[52:53] op_sel_hi:[1,0]
	v_pk_mul_f32 v[22:23], v[22:23], v[52:53] op_sel_hi:[1,0]
	v_pk_mul_f32 v[20:21], v[20:21], v[52:53] op_sel_hi:[1,0]
	v_pk_mul_f32 v[18:19], v[18:19], v[52:53] op_sel_hi:[1,0]
	s_branch .LBB0_312

; #define MFMA32(a, b, c) __builtin_amdgcn_mfma_f32_32x32x16_bf16((a), (b), (c), 0, 0, 0)
; template <int MODE, bool UNI>
; DI void attn_compute(const bf16x8 (&qf)[4], const bf16x8 (&kf)[4], const bf16x8 (&vf)[2][2], int kt, int d00, const float* lut, float ubias, AttnSt& st,
;                      unsigned W, int win, int dmask, bool lane_sel) {
;     ...
;         for (int i = 0; i < 16; ++i) { const int ci = 16 * (i >> 3) + (i & 7); bia[i] = (MODE == 4) ? lb[16 * (23 - ci)] : lb[23 - ci]; }
;     }
;     f32x16 sx;
; #pragma unroll
;     for (int i = 0; i < 16; ++i) sx[i] = 0.f;
; #pragma unroll
;     for (int ks = 0; ks < 4; ++ks) sx = MFMA32(kf[ks], qf[ks], sx);
;     asm volatile("s_waitcnt lgkmcnt(0)" ::: "memory");
;     float sv[16]; float mx = NEGF;
; #pragma unroll
;     for (int i = 0; i < 16; ++i) {
;         const int ci = 16 * (i >> 3) + (i & 7);
;         const int dist = d0 - ci;
;         bool v;
;         if (MODE == 0) v = ((W >> ci) & 1u) != 0u;
;         else if (MODE == 1) v = ((unsigned)dist <= (unsigned)win) && ((dist & dmask) == 0);
;         else if (MODE == 2) v = lane_sel;
;         else v = dist >= 0;
;         const float bias = UNI ? ubias : bia[i];
;         float s = fmaf(sx[i], SC2, bias);
;         if (MODE == 0) { const unsigned t = (unsigned)__builtin_amdgcn_sbfe((int)W, ci, 1);
;             s = __uint_as_float((__float_as_uint(s) & t) | (__float_as_uint(NEGF) & ~t)); }
;         else s = v ? s : NEGF;
;         sv[i] = s; mx = fmaxf(mx, s);
;     }
;     mx = fmaxf(mx, __shfl_xor(mx, 32));
;     const float mnew = fmaxf(st.m, mx);
;     const float msafe = (mnew > -1e29f) ? mnew : 0.f;
;     if (__ballot(mnew > st.m) != 0ull) {
;         const float alpha = __builtin_amdgcn_exp2f(st.m - msafe);
;         st.l *= alpha; st.m = mnew;
; #pragma unroll
;         for (int i = 0; i < 16; ++i) { st.o0[i] *= alpha; st.o1[i] *= alpha; }
;     }
.LBB0_324:
	s_waitcnt lgkmcnt(0)
	v_mfma_f32_32x32x16_bf16 v[34:49], v[34:37], v[62:65], 0
	v_lshrrev_b32_e32 v150, v137, v106
	v_bfe_i32 v151, v150, 4, 1
	v_bfe_i32 v152, v150, 5, 1
	v_bfe_i32 v153, v150, 6, 1
	v_mfma_f32_32x32x16_bf16 v[34:49], v[90:93], v[58:61], v[34:49]
	ds_read2_b32 v[90:91], v103 offset0:22 offset1:23
	ds_read2_b32 v[92:93], v103 offset0:20 offset1:21
	ds_read2_b32 v[106:107], v103 offset0:18 offset1:19
	ds_read2_b32 v[108:109], v103 offset0:16 offset1:17
	ds_read2_b32 v[110:111], v103 offset0:6 offset1:7
	ds_read2_b32 v[112:113], v103 offset0:4 offset1:5
	ds_read2_b32 v[146:147], v103 offset0:2 offset1:3
	ds_read2_b32 v[148:149], v103 offset1:1
	s_waitcnt lgkmcnt(0)
	v_mfma_f32_32x32x16_bf16 v[34:49], v[86:89], v[54:57], v[34:49]
	v_bfe_i32 v88, v150, 2, 1
	v_bfe_i32 v86, v150, 0, 1
	v_bfe_i32 v87, v150, 1, 1
	v_bfe_i32 v89, v150, 3, 1
	v_mfma_f32_32x32x16_bf16 v[34:49], v[82:85], v[50:53], v[34:49]
	s_waitcnt lgkmcnt(0)
	s_nop 10
	v_fmac_f32_e32 v90, 0x3e38aa3b, v35
	v_fmamk_f32 v35, v36, 0x3e38aa3b, v93
	v_fmamk_f32 v36, v38, 0x3e38aa3b, v107
	v_bitop3_b32 v83, v35, s30, v88 bitop3:0xe4
	v_fmac_f32_e32 v108, 0x3e38aa3b, v41
	v_bfe_i32 v35, v150, 7, 1
	v_fmamk_f32 v34, v34, 0x3e38aa3b, v91
	v_fmac_f32_e32 v92, 0x3e38aa3b, v37
	v_fmac_f32_e32 v106, 0x3e38aa3b, v39
	v_fmamk_f32 v37, v40, 0x3e38aa3b, v109
	v_bitop3_b32 v39, v36, s30, v151 bitop3:0xe4
	v_bitop3_b32 v40, v108, s30, v35 bitop3:0xe4
	v_fmamk_f32 v35, v42, 0x3e38aa3b, v111
	v_bfe_i32 v36, v150, 16, 1
	v_bitop3_b32 v85, v34, s30, v86 bitop3:0xe4
	v_bitop3_b32 v84, v90, s30, v87 bitop3:0xe4
	v_bitop3_b32 v41, v35, s30, v36 bitop3:0xe4
	v_fmac_f32_e32 v110, 0x3e38aa3b, v43
	v_bfe_i32 v35, v150, 17, 1
	v_bitop3_b32 v82, v92, s30, v89 bitop3:0xe4
	v_max3_f32 v34, v85, s30, v84
	v_bitop3_b32 v42, v110, s30, v35 bitop3:0xe4
	v_fmamk_f32 v35, v44, 0x3e38aa3b, v113
	v_bfe_i32 v36, v150, 18, 1
	v_bitop3_b32 v38, v106, s30, v152 bitop3:0xe4
	v_max3_f32 v34, v34, v83, v82
	v_bitop3_b32 v43, v35, s30, v36 bitop3:0xe4
	v_fmac_f32_e32 v112, 0x3e38aa3b, v45
	v_bfe_i32 v35, v150, 19, 1
	v_bitop3_b32 v37, v37, s30, v153 bitop3:0xe4
	v_max3_f32 v34, v34, v39, v38
	v_bitop3_b32 v44, v112, s30, v35 bitop3:0xe4
	v_fmamk_f32 v35, v46, 0x3e38aa3b, v147
	v_bfe_i32 v36, v150, 20, 1
	v_max3_f32 v34, v34, v37, v40
	v_bitop3_b32 v45, v35, s30, v36 bitop3:0xe4
	v_fmac_f32_e32 v146, 0x3e38aa3b, v47
	v_bfe_i32 v35, v150, 21, 1
	v_max3_f32 v34, v34, v41, v42
	v_bitop3_b32 v46, v146, s30, v35 bitop3:0xe4
	v_fmamk_f32 v35, v48, 0x3e38aa3b, v149
	v_bfe_i32 v36, v150, 22, 1
	v_max3_f32 v34, v34, v43, v44
	v_bitop3_b32 v47, v35, s30, v36 bitop3:0xe4
	v_fmac_f32_e32 v148, 0x3e38aa3b, v49
	v_bfe_i32 v35, v150, 23, 1
	v_max3_f32 v34, v34, v45, v46
	v_bitop3_b32 v35, v148, s30, v35 bitop3:0xe4
	v_max3_f32 v34, v34, v47, v35
	v_mov_b32_e32 v36, v34
	s_nop 1
	v_permlane32_swap_b32_e32 v36, v34
	s_waitcnt lgkmcnt(0)
	v_max3_f32 v34, v105, v34, v36
	v_cmp_lt_f32_e32 vcc, s12, v34
	s_nop 1
	v_cndmask_b32_e32 v36, 0, v34, vcc
	v_cmp_gt_f32_e32 vcc, v34, v105
	s_cbranch_vccz .LBB0_326
	v_sub_f32_e32 v48, v105, v36
	v_exp_f32_e32 v48, v48
	s_nop 0
	v_mul_f32_e32 v102, v102, v48
	v_pk_mul_f32 v[32:33], v[32:33], v[48:49] op_sel_hi:[1,0]
	v_pk_mul_f32 v[30:31], v[30:31], v[48:49] op_sel_hi:[1,0]
	v_pk_mul_f32 v[28:29], v[28:29], v[48:49] op_sel_hi:[1,0]
	v_pk_mul_f32 v[26:27], v[26:27], v[48:49] op_sel_hi:[1,0]
	v_pk_mul_f32 v[24:25], v[24:25], v[48:49] op_sel_hi:[1,0]
	v_pk_mul_f32 v[22:23], v[22:23], v[48:49] op_sel_hi:[1,0]
	v_pk_mul_f32 v[20:21], v[20:21], v[48:49] op_sel_hi:[1,0]
	v_pk_mul_f32 v[18:19], v[18:19], v[48:49] op_sel_hi:[1,0]
	v_pk_mul_f32 v[16:17], v[16:17], v[48:49] op_sel_hi:[1,0]
	v_pk_mul_f32 v[14:15], v[14:15], v[48:49] op_sel_hi:[1,0]
	v_pk_mul_f32 v[12:13], v[12:13], v[48:49] op_sel_hi:[1,0]
	v_pk_mul_f32 v[10:11], v[10:11], v[48:49] op_sel_hi:[1,0]
	v_pk_mul_f32 v[8:9], v[8:9], v[48:49] op_sel_hi:[1,0]
	v_pk_mul_f32 v[6:7], v[6:7], v[48:49] op_sel_hi:[1,0]
	v_pk_mul_f32 v[4:5], v[4:5], v[48:49] op_sel_hi:[1,0]
	v_pk_mul_f32 v[2:3], v[2:3], v[48:49] op_sel_hi:[1,0]
	s_branch .LBB0_327

; #define MFMA32(a, b, c) __builtin_amdgcn_mfma_f32_32x32x16_bf16((a), (b), (c), 0, 0, 0)
; template <int MODE, bool UNI>
; DI void attn_compute(const bf16x8 (&qf)[4], const bf16x8 (&kf)[4], const bf16x8 (&vf)[2][2], int kt, int d00, const float* lut, float ubias, AttnSt& st,
;                      unsigned W, int win, int dmask, bool lane_sel) {
;     ...
;         for (int i = 0; i < 16; ++i) { const int ci = 16 * (i >> 3) + (i & 7); bia[i] = (MODE == 4) ? lb[16 * (23 - ci)] : lb[23 - ci]; }
;     }
;     f32x16 sx;
; #pragma unroll
;     for (int i = 0; i < 16; ++i) sx[i] = 0.f;
; #pragma unroll
;     for (int ks = 0; ks < 4; ++ks) sx = MFMA32(kf[ks], qf[ks], sx);
;     asm volatile("s_waitcnt lgkmcnt(0)" ::: "memory");
;     float sv[16]; float mx = NEGF;
; #pragma unroll
;     for (int i = 0; i < 16; ++i) {
;         const int ci = 16 * (i >> 3) + (i & 7);
;         const int dist = d0 - ci;
;         bool v;
;         if (MODE == 0) v = ((W >> ci) & 1u) != 0u;
;         else if (MODE == 1) v = ((unsigned)dist <= (unsigned)win) && ((dist & dmask) == 0);
;         else if (MODE == 2) v = lane_sel;
;         else v = dist >= 0;
;         const float bias = UNI ? ubias : bia[i];
;         float s = fmaf(sx[i], SC2, bias);
;         if (MODE == 0) { const unsigned t = (unsigned)__builtin_amdgcn_sbfe((int)W, ci, 1);
;             s = __uint_as_float((__float_as_uint(s) & t) | (__float_as_uint(NEGF) & ~t)); }
;         else s = v ? s : NEGF;
;         sv[i] = s; mx = fmaxf(mx, s);
;     }
;     mx = fmaxf(mx, __shfl_xor(mx, 32));
;     const float mnew = fmaxf(st.m, mx);
;     const float msafe = (mnew > -1e29f) ? mnew : 0.f;
;     if (__ballot(mnew > st.m) != 0ull) {
;         const float alpha = __builtin_amdgcn_exp2f(st.m - msafe);
;         st.l *= alpha; st.m = mnew;
; #pragma unroll
;         for (int i = 0; i < 16; ++i) { st.o0[i] *= alpha; st.o1[i] *= alpha; }
;     }
.LBB0_349:
	s_waitcnt lgkmcnt(0)
	v_mfma_f32_32x32x16_bf16 v[50:65], v[50:53], v[70:73], 0
	v_add_u32_e32 v0, s65, v105
	v_mfma_f32_32x32x16_bf16 v[50:65], v[90:93], v[66:69], v[50:65]
	v_mfma_f32_32x32x16_bf16 v[50:65], v[94:97], v[78:81], v[50:65]
	ds_read2_b32 v[14:15], v0 offset0:22 offset1:23
	ds_read2_b32 v[90:91], v0 offset0:20 offset1:21
	ds_read2_b32 v[92:93], v0 offset0:18 offset1:19
	ds_read2_b32 v[94:95], v0 offset0:16 offset1:17
	ds_read2_b32 v[96:97], v0 offset0:6 offset1:7
	ds_read2_b32 v[108:109], v0 offset0:4 offset1:5
	ds_read2_b32 v[110:111], v0 offset0:2 offset1:3
	ds_read2_b32 v[112:113], v0 offset1:1
	s_waitcnt lgkmcnt(0)
	v_mfma_f32_32x32x16_bf16 v[50:65], v[86:89], v[74:77], v[50:65]
	s_waitcnt lgkmcnt(0)
	s_nop 10
	v_fmamk_f32 v0, v50, 0x3e38aa3b, v15
	v_fmac_f32_e32 v14, 0x3e38aa3b, v51
	v_fmamk_f32 v15, v52, 0x3e38aa3b, v91
	v_fmac_f32_e32 v90, 0x3e38aa3b, v53
	v_cndmask_b32_e64 v89, v239, v0, s[0:1]
	v_cndmask_b32_e64 v88, v239, v14, s[0:1]
	v_fmamk_f32 v50, v54, 0x3e38aa3b, v93
	v_fmac_f32_e32 v92, 0x3e38aa3b, v55
	v_cndmask_b32_e64 v87, v239, v15, s[0:1]
	v_cndmask_b32_e64 v86, v239, v90, s[0:1]
	v_max3_f32 v0, v89, s30, v88
	v_fmamk_f32 v51, v56, 0x3e38aa3b, v95
	v_fmac_f32_e32 v94, 0x3e38aa3b, v57
	v_fmac_f32_e32 v96, 0x3e38aa3b, v59
	v_fmamk_f32 v53, v60, 0x3e38aa3b, v109
	v_cndmask_b32_e64 v60, v239, v50, s[0:1]
	v_cndmask_b32_e64 v59, v239, v92, s[0:1]
	v_max3_f32 v0, v0, v87, v86
	v_fmamk_f32 v52, v58, 0x3e38aa3b, v97
	v_cndmask_b32_e64 v58, v239, v51, s[0:1]
	v_cndmask_b32_e64 v57, v239, v94, s[0:1]
	v_max3_f32 v0, v0, v60, v59
	v_cndmask_b32_e64 v51, v239, v52, s[0:1]
	v_cndmask_b32_e64 v50, v239, v96, s[0:1]
	v_max3_f32 v0, v0, v58, v57
	v_fmac_f32_e32 v108, 0x3e38aa3b, v61
	v_max3_f32 v0, v0, v51, v50
	v_cndmask_b32_e64 v52, v239, v53, s[0:1]
	v_cndmask_b32_e64 v53, v239, v108, s[0:1]
	v_fmamk_f32 v14, v62, 0x3e38aa3b, v111
	v_fmac_f32_e32 v110, 0x3e38aa3b, v63
	v_max3_f32 v0, v0, v52, v53
	v_cndmask_b32_e64 v54, v239, v14, s[0:1]
	v_cndmask_b32_e64 v55, v239, v110, s[0:1]
	v_fmamk_f32 v14, v64, 0x3e38aa3b, v113
	v_fmac_f32_e32 v112, 0x3e38aa3b, v65
	v_max3_f32 v0, v0, v54, v55
	v_cndmask_b32_e64 v56, v239, v14, s[0:1]
	v_cndmask_b32_e64 v14, v239, v112, s[0:1]
	v_max3_f32 v0, v0, v56, v14
	v_mov_b32_e32 v15, v0
	s_nop 1
	v_permlane32_swap_b32_e32 v15, v0
	s_waitcnt lgkmcnt(0)
	v_max3_f32 v0, v106, v0, v15
	v_cmp_lt_f32_e32 vcc, s12, v0
	s_nop 1
	v_cndmask_b32_e32 v15, 0, v0, vcc
	v_cmp_gt_f32_e32 vcc, v0, v106
	s_cbranch_vccz .LBB0_351
	v_sub_f32_e32 v61, v106, v15
	v_exp_f32_e32 v62, v61
	s_nop 0
	v_mul_f32_e32 v48, v48, v62
	v_pk_mul_f32 v[46:47], v[46:47], v[62:63] op_sel_hi:[1,0]
	v_pk_mul_f32 v[44:45], v[44:45], v[62:63] op_sel_hi:[1,0]
	v_pk_mul_f32 v[42:43], v[42:43], v[62:63] op_sel_hi:[1,0]
	v_pk_mul_f32 v[40:41], v[40:41], v[62:63] op_sel_hi:[1,0]
	v_pk_mul_f32 v[38:39], v[38:39], v[62:63] op_sel_hi:[1,0]
	v_pk_mul_f32 v[36:37], v[36:37], v[62:63] op_sel_hi:[1,0]
	v_pk_mul_f32 v[34:35], v[34:35], v[62:63] op_sel_hi:[1,0]
	v_pk_mul_f32 v[32:33], v[32:33], v[62:63] op_sel_hi:[1,0]
	v_pk_mul_f32 v[30:31], v[30:31], v[62:63] op_sel_hi:[1,0]
	v_pk_mul_f32 v[28:29], v[28:29], v[62:63] op_sel_hi:[1,0]
	v_pk_mul_f32 v[26:27], v[26:27], v[62:63] op_sel_hi:[1,0]
	v_pk_mul_f32 v[24:25], v[24:25], v[62:63] op_sel_hi:[1,0]
	v_pk_mul_f32 v[22:23], v[22:23], v[62:63] op_sel_hi:[1,0]
	v_pk_mul_f32 v[20:21], v[20:21], v[62:63] op_sel_hi:[1,0]
	v_pk_mul_f32 v[18:19], v[18:19], v[62:63] op_sel_hi:[1,0]
	v_pk_mul_f32 v[16:17], v[16:17], v[62:63] op_sel_hi:[1,0]
	s_branch .LBB0_352

; #define MFMA32(a, b, c) __builtin_amdgcn_mfma_f32_32x32x16_bf16((a), (b), (c), 0, 0, 0)
; template <int MODE, bool UNI>
; DI void attn_compute(const bf16x8 (&qf)[4], const bf16x8 (&kf)[4], const bf16x8 (&vf)[2][2], int kt, int d00, const float* lut, float ubias, AttnSt& st,
;                      unsigned W, int win, int dmask, bool lane_sel) {
;     ...
;         for (int i = 0; i < 16; ++i) { const int ci = 16 * (i >> 3) + (i & 7); bia[i] = (MODE == 4) ? lb[16 * (23 - ci)] : lb[23 - ci]; }
;     }
;     f32x16 sx;
; #pragma unroll
;     for (int i = 0; i < 16; ++i) sx[i] = 0.f;
; #pragma unroll
;     for (int ks = 0; ks < 4; ++ks) sx = MFMA32(kf[ks], qf[ks], sx);
;     asm volatile("s_waitcnt lgkmcnt(0)" ::: "memory");
;     float sv[16]; float mx = NEGF;
; #pragma unroll
;     for (int i = 0; i < 16; ++i) {
;         const int ci = 16 * (i >> 3) + (i & 7);
;         const int dist = d0 - ci;
;         bool v;
;         if (MODE == 0) v = ((W >> ci) & 1u) != 0u;
;         else if (MODE == 1) v = ((unsigned)dist <= (unsigned)win) && ((dist & dmask) == 0);
;         else if (MODE == 2) v = lane_sel;
;         else v = dist >= 0;
;         const float bias = UNI ? ubias : bia[i];
;         float s = fmaf(sx[i], SC2, bias);
;         if (MODE == 0) { const unsigned t = (unsigned)__builtin_amdgcn_sbfe((int)W, ci, 1);
;             s = __uint_as_float((__float_as_uint(s) & t) | (__float_as_uint(NEGF) & ~t)); }
;         else s = v ? s : NEGF;
;         sv[i] = s; mx = fmaxf(mx, s);
;     }
;     mx = fmaxf(mx, __shfl_xor(mx, 32));
;     const float mnew = fmaxf(st.m, mx);
;     const float msafe = (mnew > -1e29f) ? mnew : 0.f;
;     if (__ballot(mnew > st.m) != 0ull) {
;         const float alpha = __builtin_amdgcn_exp2f(st.m - msafe);
;         st.l *= alpha; st.m = mnew;
; #pragma unroll
;         for (int i = 0; i < 16; ++i) { st.o0[i] *= alpha; st.o1[i] *= alpha; }
;     }
.LBB0_361:
	s_waitcnt lgkmcnt(0)
	v_mfma_f32_32x32x16_bf16 v[50:65], v[50:53], v[70:73], 0
	v_cmp_lt_i32_e32 vcc, -1, v14
	v_mfma_f32_32x32x16_bf16 v[50:65], v[90:93], v[66:69], v[50:65]
	v_mfma_f32_32x32x16_bf16 v[50:65], v[94:97], v[78:81], v[50:65]
	ds_read2_b32 v[90:91], v15 offset0:22 offset1:23
	ds_read2_b32 v[92:93], v15 offset0:20 offset1:21
	ds_read2_b32 v[94:95], v15 offset0:18 offset1:19
	ds_read2_b32 v[96:97], v15 offset0:16 offset1:17
	ds_read2_b32 v[104:105], v15 offset0:6 offset1:7
	ds_read2_b32 v[106:107], v15 offset0:4 offset1:5
	ds_read2_b32 v[108:109], v15 offset0:2 offset1:3
	ds_read2_b32 v[110:111], v15 offset1:1
	s_waitcnt lgkmcnt(0)
	v_mfma_f32_32x32x16_bf16 v[50:65], v[86:89], v[74:77], v[50:65]
	s_waitcnt lgkmcnt(0)
	s_nop 10
	v_fmamk_f32 v49, v50, 0x3e38aa3b, v91
	v_fmac_f32_e32 v90, 0x3e38aa3b, v51
	v_fmamk_f32 v51, v54, 0x3e38aa3b, v95
	v_cndmask_b32_e32 v54, v239, v49, vcc
	v_cmp_lt_i32_e32 vcc, 0, v14
	v_fmamk_f32 v50, v52, 0x3e38aa3b, v93
	v_fmac_f32_e32 v94, 0x3e38aa3b, v55
	v_cndmask_b32_e32 v55, v239, v90, vcc
	v_cmp_lt_i32_e32 vcc, 1, v14
	v_fmac_f32_e32 v92, 0x3e38aa3b, v53
	v_fmamk_f32 v53, v56, 0x3e38aa3b, v97
	v_cndmask_b32_e32 v56, v239, v50, vcc
	v_cmp_lt_i32_e32 vcc, 2, v14
	v_fmac_f32_e32 v96, 0x3e38aa3b, v57
	v_fmac_f32_e32 v104, 0x3e38aa3b, v59
	v_cndmask_b32_e32 v50, v239, v92, vcc
	v_cmp_lt_i32_e32 vcc, 3, v14
	v_max3_f32 v49, v54, s30, v55
	v_max3_f32 v49, v49, v56, v50
	v_cndmask_b32_e32 v51, v239, v51, vcc
	v_cmp_lt_i32_e32 vcc, 4, v14
	v_fmac_f32_e32 v106, 0x3e38aa3b, v61
	v_fmac_f32_e32 v108, 0x3e38aa3b, v63
	v_cndmask_b32_e32 v52, v239, v94, vcc
	v_cmp_lt_i32_e32 vcc, 5, v14
	v_max3_f32 v49, v49, v51, v52
	v_fmac_f32_e32 v110, 0x3e38aa3b, v65
	v_cndmask_b32_e32 v86, v239, v53, vcc
	v_cmp_lt_i32_e32 vcc, 6, v14
	v_fmamk_f32 v53, v58, 0x3e38aa3b, v105
	s_nop 0
	v_cndmask_b32_e32 v87, v239, v96, vcc
	v_cmp_lt_i32_e32 vcc, 15, v14
	v_max3_f32 v49, v49, v86, v87
	s_nop 0
	v_cndmask_b32_e32 v58, v239, v53, vcc
	v_cmp_lt_i32_e32 vcc, 16, v14
	v_fmamk_f32 v53, v60, 0x3e38aa3b, v107
	s_nop 0
	v_cndmask_b32_e32 v59, v239, v104, vcc
	v_cmp_lt_i32_e32 vcc, 17, v14
	v_max3_f32 v49, v49, v58, v59
	s_nop 0
	v_cndmask_b32_e32 v60, v239, v53, vcc
	v_cmp_lt_i32_e32 vcc, 18, v14
	v_fmamk_f32 v53, v62, 0x3e38aa3b, v109
	s_nop 0
	v_cndmask_b32_e32 v61, v239, v106, vcc
	v_cmp_lt_i32_e32 vcc, 19, v14
	v_max3_f32 v49, v49, v60, v61
	s_nop 0
	v_cndmask_b32_e32 v62, v239, v53, vcc
	v_cmp_lt_i32_e32 vcc, 20, v14
	v_fmamk_f32 v53, v64, 0x3e38aa3b, v111
	s_nop 0
	v_cndmask_b32_e32 v63, v239, v108, vcc
	v_cmp_lt_i32_e32 vcc, 21, v14
	v_max3_f32 v49, v49, v62, v63
	s_nop 0
	v_cndmask_b32_e32 v64, v239, v53, vcc
	v_cmp_lt_i32_e32 vcc, 22, v14
	s_nop 1
	v_cndmask_b32_e32 v53, v239, v110, vcc
	v_max3_f32 v49, v49, v64, v53
	v_mov_b32_e32 v57, v49
	s_nop 1
	v_permlane32_swap_b32_e32 v57, v49
	s_waitcnt lgkmcnt(0)
	v_max3_f32 v49, v0, v49, v57
	v_cmp_lt_f32_e32 vcc, s12, v49
	s_nop 1
	v_cndmask_b32_e32 v57, 0, v49, vcc
	v_cmp_gt_f32_e32 vcc, v49, v0
	s_cbranch_vccz .LBB0_363
	v_sub_f32_e32 v0, v0, v57
	v_exp_f32_e32 v0, v0
	s_nop 0
	v_mul_f32_e32 v48, v48, v0
	v_pk_mul_f32 v[46:47], v[46:47], v[0:1] op_sel_hi:[1,0]
	v_pk_mul_f32 v[44:45], v[44:45], v[0:1] op_sel_hi:[1,0]
	v_pk_mul_f32 v[42:43], v[42:43], v[0:1] op_sel_hi:[1,0]
	v_pk_mul_f32 v[40:41], v[40:41], v[0:1] op_sel_hi:[1,0]
	v_pk_mul_f32 v[38:39], v[38:39], v[0:1] op_sel_hi:[1,0]
	v_pk_mul_f32 v[36:37], v[36:37], v[0:1] op_sel_hi:[1,0]
	v_pk_mul_f32 v[34:35], v[34:35], v[0:1] op_sel_hi:[1,0]
	v_pk_mul_f32 v[32:33], v[32:33], v[0:1] op_sel_hi:[1,0]
	v_pk_mul_f32 v[30:31], v[30:31], v[0:1] op_sel_hi:[1,0]
	v_pk_mul_f32 v[28:29], v[28:29], v[0:1] op_sel_hi:[1,0]
	v_pk_mul_f32 v[26:27], v[26:27], v[0:1] op_sel_hi:[1,0]
	v_pk_mul_f32 v[24:25], v[24:25], v[0:1] op_sel_hi:[1,0]
	v_pk_mul_f32 v[22:23], v[22:23], v[0:1] op_sel_hi:[1,0]
	v_pk_mul_f32 v[20:21], v[20:21], v[0:1] op_sel_hi:[1,0]
	v_pk_mul_f32 v[18:19], v[18:19], v[0:1] op_sel_hi:[1,0]
	v_pk_mul_f32 v[16:17], v[16:17], v[0:1] op_sel_hi:[1,0]
	s_branch .LBB0_364
